# diff-attention loop: K/V^T LDS-DMA loads use SGPR-pair base + 32-bit running offset (12 fewer 64-bit VALU adds per trip)
# speedup vs baseline: 1.0086x; 1.0086x over previous
; __device__ __forceinline__ void dattn_unit(LAS unsigned char* lds, const bf16_t* Qp, const bf16_t* Kp, const bf16_t* Vtp, int qb, bf16_t* Op, const float* lq1, const float* lk1, const float* lq2, const float* lk2, const float* subg, float outscale, int tid) {
;     ...
;     const int q15 = qi & 15;
;     const int kx0 = qi * 256 + (((c * 8 + hh) ^ q15) << 4);
;     const int vx = qi * 128 + ((hh ^ ((qi >> 1) & 7)) << 4);
.LBB0_215:
	s_add_i32 s6, s5, 0x4000
	s_and_b32 s6, s6, 0xc000
	s_add_i32 s7, s15, s6
	s_add_i32 s6, s16, s6
	s_mov_b32 s98, s7
	s_mov_b32 s99, s6
	s_waitcnt vmcnt(4)
	s_barrier
	s_add_u32 s100, s74, s36
	s_addc_u32 s101, s75, s37
	s_add_u32 s34, s74, s58
	s_addc_u32 s35, s75, s59
	s_add_i32 s6, s5, 0xffff8000
	s_and_b32 s6, s6, 0x8000
	s_add_i32 s7, s6, 0
	v_add_u32_e32 v0, s7, v230
	ds_read_b128 v[68:71], v0 offset:16384
	ds_read_b128 v[72:75], v0 offset:24576
	v_add_u32_e32 v0, s7, v231
	ds_read_b128 v[76:79], v0 offset:16384
	ds_read_b128 v[162:165], v0 offset:24576
	v_max3_f32 v240, v98, v82, v99
	v_max3_f32 v66, v83, v100, v84
	s_waitcnt lgkmcnt(0)
	v_mfma_f32_32x32x16_bf16 v[146:161], v[68:71], v[190:193], v[114:129]
	v_add_u32_e32 v0, s7, v229
	v_max3_f32 v240, v240, v101, v85
	v_max3_f32 v66, v66, v102, v86
	v_mfma_f32_32x32x16_bf16 v[130:145], v[72:75], v[190:193], v[114:129]
	s_mov_b32 m0, s98
	s_nop 0
	global_load_lds_dwordx4 v206, s[100:101]
	ds_read_b128 v[68:71], v0 offset:16384
	ds_read_b128 v[72:75], v0 offset:24576
	v_add_u32_e32 v0, s7, v233
	v_max3_f32 v240, v240, v103, v87
	v_max3_f32 v66, v66, v104, v88
	v_mfma_f32_32x32x16_bf16 v[146:161], v[76:79], v[186:189], v[146:161]
	ds_read_b128 v[76:79], v0 offset:16384
	ds_read_b128 v[166:169], v0 offset:24576
	v_max3_f32 v240, v240, v105, v89
	v_max3_f32 v66, v66, v106, v90
	v_mfma_f32_32x32x16_bf16 v[130:145], v[162:165], v[186:189], v[130:145]
	s_waitcnt lgkmcnt(0)
	v_max3_f32 v240, v240, v107, v91
	v_max3_f32 v66, v66, v108, v92
	v_mfma_f32_32x32x16_bf16 v[146:161], v[68:71], v[182:185], v[146:161]
	v_max3_f32 v240, v240, v109, v93
	v_max3_f32 v66, v66, v110, v94
	v_mfma_f32_32x32x16_bf16 v[130:145], v[72:75], v[182:185], v[130:145]
	s_mov_b32 m0, s99
	s_nop 0
	global_load_lds_dwordx4 v80, s[34:35]
	v_max3_f32 v240, v240, v111, v95
	v_max3_f32 v66, v66, v112, v96
	v_mfma_f32_32x32x16_bf16 v[146:161], v[76:79], v[178:181], v[146:161]
	v_max3_f32 v240, v240, v113, v97
	v_max3_f32 v240, v240, v66, v66
	v_mfma_f32_32x32x16_bf16 v[130:145], v[166:169], v[178:181], v[130:145]
	s_add_i32 s7, s7, 0x10000
	v_add_u32_e32 v0, s7, v227
	ds_read_b128 v[194:197], v0
	ds_read_b128 v[76:79], v0 offset:4096
	ds_read_b128 v[72:75], v0 offset:8192
	ds_read_b128 v[68:71], v0 offset:12288
	v_mov_b32_e32 v66, v240
	s_nop 1
	v_permlane32_swap_b32_e32 v240, v66
	v_max3_f32 v198, v240, v66, v66
	s_nop 0
	v_pk_add_f32 v[162:163], v[200:201], v[198:199]
	s_nop 0
	v_cmp_gt_f32_e32 vcc, v162, v163
	s_nop 1
	v_cndmask_b32_e32 v0, v201, v162, vcc
	v_cmp_gt_f32_e32 vcc, v0, v201
	s_cbranch_vccz .LBB0_226
	v_sub_f32_e32 v66, v201, v0
	v_exp_f32_e32 v66, v66
	v_xor_b32_e32 v162, 0x80000000, v0
	v_mov_b32_e32 v163, v162
	v_mov_b32_e32 v164, v162
	v_pk_mul_f32 v[64:65], v[64:65], v[66:67] op_sel_hi:[1,0]
	v_pk_mul_f32 v[62:63], v[62:63], v[66:67] op_sel_hi:[1,0]
	v_pk_mul_f32 v[60:61], v[60:61], v[66:67] op_sel_hi:[1,0]
	v_pk_mul_f32 v[58:59], v[58:59], v[66:67] op_sel_hi:[1,0]
	v_pk_mul_f32 v[56:57], v[56:57], v[66:67] op_sel_hi:[1,0]
	v_pk_mul_f32 v[54:55], v[54:55], v[66:67] op_sel_hi:[1,0]
	v_pk_mul_f32 v[52:53], v[52:53], v[66:67] op_sel_hi:[1,0]
	v_pk_mul_f32 v[50:51], v[50:51], v[66:67] op_sel_hi:[1,0]
	v_pk_mul_f32 v[48:49], v[48:49], v[66:67] op_sel_hi:[1,0]
	v_pk_mul_f32 v[46:47], v[46:47], v[66:67] op_sel_hi:[1,0]
	v_pk_mul_f32 v[44:45], v[44:45], v[66:67] op_sel_hi:[1,0]
	v_pk_mul_f32 v[42:43], v[42:43], v[66:67] op_sel_hi:[1,0]
	v_pk_mul_f32 v[40:41], v[40:41], v[66:67] op_sel_hi:[1,0]
	v_pk_mul_f32 v[38:39], v[38:39], v[66:67] op_sel_hi:[1,0]
	v_pk_mul_f32 v[36:37], v[36:37], v[66:67] op_sel_hi:[1,0]
	v_pk_mul_f32 v[34:35], v[34:35], v[66:67] op_sel_hi:[1,0]
	v_pk_mul_f32 v[32:33], v[32:33], v[66:67] op_sel_hi:[1,0]
	v_pk_mul_f32 v[30:31], v[30:31], v[66:67] op_sel_hi:[1,0]
	v_pk_mul_f32 v[28:29], v[28:29], v[66:67] op_sel_hi:[1,0]
	v_pk_mul_f32 v[26:27], v[26:27], v[66:67] op_sel_hi:[1,0]
	v_pk_mul_f32 v[24:25], v[24:25], v[66:67] op_sel_hi:[1,0]
	v_pk_mul_f32 v[22:23], v[22:23], v[66:67] op_sel_hi:[1,0]
	v_pk_mul_f32 v[20:21], v[20:21], v[66:67] op_sel_hi:[1,0]
	v_pk_mul_f32 v[18:19], v[18:19], v[66:67] op_sel_hi:[1,0]
	v_pk_mul_f32 v[16:17], v[16:17], v[66:67] op_sel_hi:[1,0]
	v_pk_mul_f32 v[14:15], v[14:15], v[66:67] op_sel_hi:[1,0]
	v_pk_mul_f32 v[12:13], v[12:13], v[66:67] op_sel_hi:[1,0]
	v_pk_mul_f32 v[10:11], v[10:11], v[66:67] op_sel_hi:[1,0]
	v_pk_mul_f32 v[8:9], v[8:9], v[66:67] op_sel_hi:[1,0]
	v_pk_mul_f32 v[6:7], v[6:7], v[66:67] op_sel_hi:[1,0]
	v_pk_mul_f32 v[4:5], v[4:5], v[66:67] op_sel_hi:[1,0]
	v_pk_mul_f32 v[2:3], v[2:3], v[66:67] op_sel_hi:[1,0]
	v_mul_f32_e32 v232, v232, v66
	v_mov_b32_e32 v165, v162
	v_mov_b32_e32 v166, v162
	v_mov_b32_e32 v167, v162
	v_mov_b32_e32 v168, v162
	v_mov_b32_e32 v169, v162
	v_mov_b32_e32 v170, v162
	v_mov_b32_e32 v171, v162
	v_mov_b32_e32 v172, v162
	v_mov_b32_e32 v173, v162
	v_mov_b32_e32 v174, v162
	v_mov_b32_e32 v175, v162
	v_mov_b32_e32 v176, v162
	v_mov_b32_e32 v177, v162
	v_mov_b32_e32 v201, v0
	v_mov_b32_e32 v66, v162
	v_mov_b32_e32 v115, v162
	v_mov_b32_e32 v116, v162
	v_mov_b32_e32 v117, v162
	v_mov_b32_e32 v118, v162
	v_mov_b32_e32 v119, v162
	v_mov_b32_e32 v120, v162
	v_mov_b32_e32 v121, v162
	v_mov_b32_e32 v122, v162
	v_mov_b32_e32 v123, v162
	v_mov_b32_e32 v124, v162
	v_mov_b32_e32 v125, v162
	v_mov_b32_e32 v126, v162
	v_mov_b32_e32 v127, v162
	v_mov_b32_e32 v128, v162
	v_mov_b32_e32 v129, v162
	v_sub_f32_e32 v0, v0, v200
	v_cmp_neq_f32_e32 vcc, 0, v0
	s_cbranch_vccz .LBB0_218

; #define DA_WAIT_BAR(N) do { asm volatile("s_waitcnt vmcnt(" #N ")" ::: "memory"); __builtin_amdgcn_s_barrier(); } while (0)
; __device__ __forceinline__ void dattn_unit(LAS unsigned char* lds, const bf16_t* Qp, const bf16_t* Kp, const bf16_t* Vtp, int qb, bf16_t* Op, const float* lq1, const float* lk1, const float* lq2, const float* lk2, const float* subg, float outscale, int tid) {
;     ...
;     DA_DMA(0, 0); DA_DMA(1, 1); if (nk > 2) DA_DMA(2, 2);
;     asm volatile("s_waitcnt vmcnt(0)" ::: "memory"); __builtin_amdgcn_s_barrier();
;     f32x16 sa[2], sb[2]; f32x16 negm; float mra = 0.f, mrb = 0.f;
; #pragma unroll
;     for (int i = 0; i < 16; ++i) negm[i] = 0.f;
;     DA_QK(sa, mra, 0);
;     for (int kt = 0; kt < nfull; kt += 2) {
;         DA_WAIT_BAR(4); DA_DMA(kt + 3, (kt + 3) & 3); DA_QK(sb, mrb, (kt + 1) & 3); DA_SOFTMAX_PV(sa, mra, kt & 3, false, kt);
;         DA_WAIT_BAR(4); if (kt + 4 < nk) DA_DMA(kt + 4, kt & 3); DA_QK(sa, mra, (kt + 2) & 3); DA_SOFTMAX_PV(sb, mrb, (kt + 1) & 3, false, kt + 1);
.LBB0_218:
	v_exp_f32_e32 v198, v98
	v_exp_f32_e32 v0, v99
	v_exp_f32_e32 v200, v100
	v_exp_f32_e32 v98, v101
	v_exp_f32_e32 v238, v102
	v_exp_f32_e32 v99, v103
	v_exp_f32_e32 v239, v104
	v_exp_f32_e32 v100, v105
	v_cvt_pk_bf16_f32 v240, v198, v0
	v_cvt_pk_bf16_f32 v241, v200, v98
	v_cvt_pk_bf16_f32 v242, v238, v99
	v_cvt_pk_bf16_f32 v243, v239, v100
	v_exp_f32_e32 v105, v106
	s_waitcnt lgkmcnt(0)
	v_mfma_f32_32x32x16_bf16 v[50:65], v[194:197], v[240:243], v[50:65]
	v_add_u32_e32 v248, s7, v219
	v_exp_f32_e32 v101, v107
	v_exp_f32_e32 v106, v108
	v_exp_f32_e32 v102, v109
	v_mfma_f32_32x32x16_bf16 v[34:49], v[76:79], v[240:243], v[34:49]
	s_add_i32 m0, s98, 0x2000
	s_nop 0
	global_load_lds_dwordx4 v204, s[100:101]
	v_exp_f32_e32 v107, v110
	v_exp_f32_e32 v103, v111
	v_exp_f32_e32 v108, v112
	v_mfma_f32_32x32x16_bf16 v[18:33], v[72:75], v[240:243], v[18:33]
	ds_read_b128 v[72:75], v248
	ds_read_b128 v[76:79], v248 offset:4096
	ds_read_b128 v[194:197], v248 offset:8192
	ds_read_b128 v[220:223], v248 offset:12288
	v_exp_f32_e32 v104, v113
	v_cvt_pk_bf16_f32 v244, v105, v101
	v_cvt_pk_bf16_f32 v245, v106, v102
	v_mfma_f32_32x32x16_bf16 v[2:17], v[68:71], v[240:243], v[2:17]
	v_cvt_pk_bf16_f32 v246, v107, v103
	v_cvt_pk_bf16_f32 v247, v108, v104
	v_exp_f32_e32 v109, v82
	v_exp_f32_e32 v82, v83
	s_waitcnt lgkmcnt(0)
	v_mfma_f32_32x32x16_bf16 v[50:65], v[72:75], v[244:247], v[50:65]
	v_add_u32_e32 v248, s7, v218
	v_exp_f32_e32 v110, v84
	v_exp_f32_e32 v83, v85
	v_exp_f32_e32 v111, v86
	v_mfma_f32_32x32x16_bf16 v[34:49], v[76:79], v[244:247], v[34:49]
	s_add_i32 m0, s99, 0x2000
	s_nop 0
	global_load_lds_dwordx4 v202, s[34:35]
	v_exp_f32_e32 v84, v87
	v_exp_f32_e32 v112, v88
	v_exp_f32_e32 v85, v89
	v_mfma_f32_32x32x16_bf16 v[18:33], v[194:197], v[244:247], v[18:33]
	ds_read_b128 v[68:71], v248
	ds_read_b128 v[72:75], v248 offset:4096
	ds_read_b128 v[76:79], v248 offset:8192
	ds_read_b128 v[194:197], v248 offset:12288
	v_exp_f32_e32 v90, v90
	v_exp_f32_e32 v86, v91
	v_exp_f32_e32 v91, v92
	v_mfma_f32_32x32x16_bf16 v[2:17], v[220:223], v[244:247], v[2:17]
	v_exp_f32_e32 v87, v93
	v_exp_f32_e32 v92, v94
	v_exp_f32_e32 v88, v95
	v_exp_f32_e32 v93, v96
	v_exp_f32_e32 v89, v97
	v_cvt_pk_bf16_f32 v94, v109, v82
	v_cvt_pk_bf16_f32 v95, v110, v83
	v_cvt_pk_bf16_f32 v96, v111, v84
	v_cvt_pk_bf16_f32 v97, v112, v85
	v_add_f32_e32 v240, 0, v198
	v_add_f32_e32 v241, 0, v0
	s_waitcnt lgkmcnt(0)
	v_mfma_f32_32x32x16_bf16 v[50:65], v[68:71], v[94:97], v[50:65]
	v_add_u32_e32 v113, s7, v217
	v_cvt_pk_bf16_f32 v248, v90, v86
	v_cvt_pk_bf16_f32 v249, v91, v87
	v_add_f32_e32 v240, v200, v240
	v_add_f32_e32 v241, v98, v241
	v_add_f32_e32 v240, v238, v240
	v_mfma_f32_32x32x16_bf16 v[34:49], v[72:75], v[94:97], v[34:49]
	v_cvt_pk_bf16_f32 v250, v92, v88
	v_cvt_pk_bf16_f32 v251, v93, v89
	v_add_f32_e32 v241, v99, v241
	v_add_f32_e32 v240, v239, v240
	v_add_f32_e32 v241, v100, v241
	v_mfma_f32_32x32x16_bf16 v[18:33], v[76:79], v[94:97], v[18:33]
	ds_read_b128 v[68:71], v113
	ds_read_b128 v[72:75], v113 offset:4096
	ds_read_b128 v[76:79], v113 offset:8192
	ds_read_b128 v[220:223], v113 offset:12288
	v_add_f32_e32 v240, v105, v240
	v_add_f32_e32 v241, v101, v241
	v_add_f32_e32 v240, v106, v240
	v_add_f32_e32 v241, v102, v241
	v_mfma_f32_32x32x16_bf16 v[2:17], v[194:197], v[94:97], v[2:17]
	v_add_f32_e32 v240, v107, v240
	v_add_f32_e32 v241, v103, v241
	v_add_f32_e32 v240, v108, v240
	v_add_f32_e32 v241, v104, v241
	v_add_f32_e32 v240, v109, v240
	v_add_f32_e32 v241, v82, v241
	s_waitcnt lgkmcnt(0)
	v_mfma_f32_32x32x16_bf16 v[50:65], v[68:71], v[248:251], v[50:65]
	v_add_f32_e32 v240, v110, v240
	v_add_f32_e32 v241, v83, v241
	v_add_f32_e32 v240, v111, v240
	v_add_f32_e32 v241, v84, v241
	v_add_f32_e32 v240, v112, v240
	v_add_f32_e32 v241, v85, v241
	v_mfma_f32_32x32x16_bf16 v[34:49], v[72:75], v[248:251], v[34:49]
	v_add_f32_e32 v240, v90, v240
	v_add_f32_e32 v241, v86, v241
	v_add_f32_e32 v240, v91, v240
	v_add_f32_e32 v241, v87, v241
	v_add_f32_e32 v240, v92, v240
	v_add_f32_e32 v241, v88, v241
	v_mfma_f32_32x32x16_bf16 v[18:33], v[76:79], v[248:251], v[18:33]
	v_add_f32_e32 v240, v93, v240
	v_add_f32_e32 v241, v89, v241
	v_add_f32_e32 v0, v241, v240
	v_add_f32_e32 v0, v232, v0
	v_mfma_f32_32x32x16_bf16 v[2:17], v[220:223], v[248:251], v[2:17]
	s_waitcnt vmcnt(4)
	s_add_i32 s17, s4, 4
	s_cmp_gt_u32 s17, s11
	s_barrier
	s_cbranch_scc1 .LBB0_220
	s_add_i32 s17, s15, s6
	s_add_i32 s7, s7, s14
	s_add_u32 s100, s74, s22
	s_addc_u32 s101, s75, s23
	s_add_u32 s34, s74, 0x20400200
	s_addc_u32 s35, s75, 0
	s_mov_b32 m0, s17
	s_nop 0
	global_load_lds_dwordx4 v206, s[100:101]
	s_mov_b32 m0, s7
	s_nop 0
	global_load_lds_dwordx4 v80, s[34:35]
	s_add_i32 m0, s17, 0x2000
	s_nop 0
	global_load_lds_dwordx4 v204, s[100:101]
	s_add_i32 m0, s7, 0x2000
	s_nop 0
	global_load_lds_dwordx4 v202, s[34:35]
